# first K trip of every GEMM unit peeled with C=0 MFMAs, the 128-register accumulator clear per unit removed
# speedup vs baseline: 1.0136x; 1.0108x over previous
; #define PG8_STAGE(bufoff, gbase, voff) do { _Pragma("unroll") for (int _i = 0; _i < 2; ++_i) \
;         __builtin_amdgcn_global_load_lds((const unsigned*)((const char*)(gbase) + (voff)[_i]), (LAS unsigned*)(lds + (bufoff) + ldsw + _i * 8192), 16, 0, 0); } while (0)
; #define PG8_LDA(dst, b, h) do { _Pragma("unroll") for (int m = 0; m < 4; ++m) _Pragma("unroll") for (int k = 0; k < 2; ++k) dst[m][k] = *(const LAS bf16x8*)(lds + PG8_SA(b, h) + aoff + m * 2048 + k * 1024); } while (0)
; #define PG8_LDB(dst, b, h) do { _Pragma("unroll") for (int n = 0; n < 2; ++n) _Pragma("unroll") for (int k = 0; k < 2; ++k) dst[n][k] = *(const LAS bf16x8*)(lds + PG8_SB(b, h) + boff + n * 2048 + k * 1024); } while (0)
; #define PG8_MMA(ai, bj, At, Bt) do { __builtin_amdgcn_s_setprio(1); _Pragma("unroll") for (int m = 0; m < 4; ++m) _Pragma("unroll") for (int n = 0; n < 2; ++n) _Pragma("unroll") for (int k = 0; k < 2; ++k) \
;         acc[ai][bj][m][n] = __builtin_amdgcn_mfma_f32_16x16x32_bf16(Bt[n][k], At[m][k], acc[ai][bj][m][n], 0, 0, 0); __builtin_amdgcn_s_setprio(0); } while (0)
; #define PG8_WAIT_L(n) asm volatile("s_waitcnt lgkmcnt(" #n ")" ::: "memory")
; #define PG8_BAR __builtin_amdgcn_s_barrier()
; #define PG8_SCHED __builtin_amdgcn_sched_barrier(0)
; template <class EpiFn>
; DI void gemm_phase(LAS unsigned char* lds, const Sched& S, const bool perm, const EpiFn& E) {
;     ...
;             PG8_LDB(B0, 0, 0); PG8_SCHED; PG8_LDA(At, 0, 0); PG8_STAGE(PG8_SA(1, 1), a1 + hstep, voffA);
;             PG8_WAIT_L(8); PG8_BAR; PG8_WAIT_L(0); PG8_MMA(0, 0, At, B0); PG8_BAR; PG8_SCHED;
;             PG8_LDB(B1, 0, 1); PG8_STAGE(PG8_SB(0, 0), b2, voffB);
;             PG8_BAR; PG8_WAIT_L(0); PG8_MMA(0, 1, At, B1); PG8_BAR;
;             PG8_LDA(At, 0, 1); PG8_STAGE(PG8_SA(0, 0), a2, voffA);
;             PG8_BAR; PG8_WAIT_L(0); PG8_MMA(1, 0, At, B0); PG8_BAR; PG8_SCHED;
.LBB0_394:
	s_cmp_lg_u32 s43, 0
	s_cselect_b64 s[28:29], -1, 0
	s_cmp_eq_u32 s43, 0
	s_cselect_b32 s16, s24, s86
	s_add_i32 s17, s16, -2
	s_add_u32 s6, s40, 0x80
	s_addc_u32 s7, s41, 0
	s_add_u32 s18, s8, 0x100
	s_mov_b32 s60, 0
	s_addc_u32 s51, s9, 0
	s_add_i32 s61, s60, 2
	s_add_u32 s8, s6, 0x80
	s_addc_u32 s9, s7, 0
	s_add_i32 s62, 0, 0x10000
	v_add_u32_e32 v0, s62, v222
	ds_read_b128 v[130:133], v0
	ds_read_b128 v[134:137], v0 offset:1024
	ds_read_b128 v[138:141], v0 offset:2048
	ds_read_b128 v[142:145], v0 offset:3072
	s_cmp_eq_u32 s17, s60
	s_cselect_b32 s9, s13, s9
	s_cselect_b32 s8, s12, s8
	s_cselect_b32 s41, s39, s51
	s_cselect_b32 s40, s38, s18
	v_lshl_add_u64 v[178:179], s[6:7], 0, v[196:197]
	s_add_i32 m0, s26, 0xc000
	ds_read_b128 v[146:149], v228
	ds_read_b128 v[150:153], v228 offset:1024
	ds_read_b128 v[154:157], v228 offset:2048
	ds_read_b128 v[158:161], v228 offset:3072
	ds_read_b128 v[162:165], v228 offset:4096
	ds_read_b128 v[166:169], v228 offset:5120
	ds_read_b128 v[170:173], v228 offset:6144
	ds_read_b128 v[174:177], v228 offset:7168
	global_load_lds_dwordx4 v[178:179], off
	v_lshl_add_u64 v[178:179], s[6:7], 0, v[198:199]
	s_add_i32 m0, s26, 0xe000
	s_nop 0
	global_load_lds_dwordx4 v[178:179], off
	s_waitcnt lgkmcnt(8)
	s_barrier
	s_waitcnt lgkmcnt(0)
	s_setprio 1
	s_waitcnt lgkmcnt(0)
	v_mfma_f32_16x16x32_bf16 v[118:121], v[130:133], v[146:149], 0
	v_mfma_f32_16x16x32_bf16 v[106:109], v[138:141], v[146:149], 0
	v_mfma_f32_16x16x32_bf16 v[50:53], v[130:133], v[154:157], 0
	v_mfma_f32_16x16x32_bf16 v[42:45], v[138:141], v[154:157], 0
	v_mfma_f32_16x16x32_bf16 v[30:33], v[130:133], v[162:165], 0
	v_mfma_f32_16x16x32_bf16 v[26:29], v[138:141], v[162:165], 0
	v_mfma_f32_16x16x32_bf16 v[14:17], v[130:133], v[170:173], 0
	v_mfma_f32_16x16x32_bf16 v[10:13], v[138:141], v[170:173], 0
	v_mfma_f32_16x16x32_bf16 v[118:121], v[134:137], v[150:153], v[118:121]
	v_mfma_f32_16x16x32_bf16 v[106:109], v[142:145], v[150:153], v[106:109]
	v_mfma_f32_16x16x32_bf16 v[50:53], v[134:137], v[158:161], v[50:53]
	v_mfma_f32_16x16x32_bf16 v[42:45], v[142:145], v[158:161], v[42:45]
	v_mfma_f32_16x16x32_bf16 v[30:33], v[134:137], v[166:169], v[30:33]
	v_mfma_f32_16x16x32_bf16 v[26:29], v[142:145], v[166:169], v[26:29]
	v_mfma_f32_16x16x32_bf16 v[14:17], v[134:137], v[174:177], v[14:17]
	v_mfma_f32_16x16x32_bf16 v[10:13], v[142:145], v[174:177], v[10:13]
	s_setprio 0
	s_barrier
	s_add_i32 s60, 0, 0x14000
	s_add_i32 s62, s62, s75
	v_add_u32_e32 v0, s60, v222
	v_lshl_add_u64 v[208:209], s[40:41], 0, v[192:193]
	s_mov_b32 m0, s62
	ds_read_b128 v[178:181], v0
	ds_read_b128 v[182:185], v0 offset:1024
	ds_read_b128 v[200:203], v0 offset:2048
	ds_read_b128 v[204:207], v0 offset:3072
	global_load_lds_dwordx4 v[208:209], off
	v_lshl_add_u64 v[230:231], s[40:41], 0, v[188:189]
	s_add_i32 m0, s62, 0x2000
	s_nop 0
	global_load_lds_dwordx4 v[230:231], off
	s_barrier
	s_waitcnt lgkmcnt(0)
	s_setprio 1
	s_waitcnt lgkmcnt(0)
	v_mfma_f32_16x16x32_bf16 v[70:73], v[178:181], v[146:149], 0
	v_mfma_f32_16x16x32_bf16 v[58:61], v[200:203], v[146:149], 0
	v_mfma_f32_16x16x32_bf16 v[38:41], v[178:181], v[154:157], 0
	v_mfma_f32_16x16x32_bf16 v[34:37], v[200:203], v[154:157], 0
	v_mfma_f32_16x16x32_bf16 v[22:25], v[178:181], v[162:165], 0
	v_mfma_f32_16x16x32_bf16 v[18:21], v[200:203], v[162:165], 0
	v_mfma_f32_16x16x32_bf16 v[6:9], v[178:181], v[170:173], 0
	v_mfma_f32_16x16x32_bf16 v[2:5], v[200:203], v[170:173], 0
	v_mfma_f32_16x16x32_bf16 v[70:73], v[182:185], v[150:153], v[70:73]
	v_mfma_f32_16x16x32_bf16 v[58:61], v[204:207], v[150:153], v[58:61]
	v_mfma_f32_16x16x32_bf16 v[38:41], v[182:185], v[158:161], v[38:41]
	v_mfma_f32_16x16x32_bf16 v[34:37], v[204:207], v[158:161], v[34:37]
	v_mfma_f32_16x16x32_bf16 v[22:25], v[182:185], v[166:169], v[22:25]
	v_mfma_f32_16x16x32_bf16 v[18:21], v[204:207], v[166:169], v[18:21]
	v_mfma_f32_16x16x32_bf16 v[6:9], v[182:185], v[174:177], v[6:9]
	v_mfma_f32_16x16x32_bf16 v[2:5], v[204:207], v[174:177], v[2:5]
	s_setprio 0
	s_mov_b32 m0, s26
	v_lshl_add_u64 v[232:233], s[8:9], 0, v[190:191]
	s_barrier
	ds_read_b128 v[146:149], v228 offset:16384
	ds_read_b128 v[150:153], v228 offset:17408
	ds_read_b128 v[154:157], v228 offset:18432
	ds_read_b128 v[158:161], v228 offset:19456
	ds_read_b128 v[162:165], v228 offset:20480
	ds_read_b128 v[166:169], v228 offset:21504
	ds_read_b128 v[170:173], v228 offset:22528
	ds_read_b128 v[174:177], v228 offset:23552
	global_load_lds_dwordx4 v[232:233], off
	v_lshl_add_u64 v[234:235], s[8:9], 0, v[186:187]
	s_mov_b32 m0, s57
	s_nop 0
	global_load_lds_dwordx4 v[234:235], off
	s_barrier
	s_waitcnt lgkmcnt(0)
	s_setprio 1
	s_waitcnt lgkmcnt(0)
	v_mfma_f32_16x16x32_bf16 v[126:129], v[130:133], v[146:149], 0
	v_mfma_f32_16x16x32_bf16 v[122:125], v[138:141], v[146:149], 0
	v_mfma_f32_16x16x32_bf16 v[114:117], v[130:133], v[154:157], 0
	v_mfma_f32_16x16x32_bf16 v[110:113], v[138:141], v[154:157], 0
	v_mfma_f32_16x16x32_bf16 v[98:101], v[130:133], v[162:165], 0
	v_mfma_f32_16x16x32_bf16 v[90:93], v[138:141], v[162:165], 0
	v_mfma_f32_16x16x32_bf16 v[82:85], v[130:133], v[170:173], 0
	v_mfma_f32_16x16x32_bf16 v[74:77], v[138:141], v[170:173], 0
	v_mfma_f32_16x16x32_bf16 v[126:129], v[134:137], v[150:153], v[126:129]
	v_mfma_f32_16x16x32_bf16 v[122:125], v[142:145], v[150:153], v[122:125]
	v_mfma_f32_16x16x32_bf16 v[114:117], v[134:137], v[158:161], v[114:117]
	v_mfma_f32_16x16x32_bf16 v[110:113], v[142:145], v[158:161], v[110:113]
	v_mfma_f32_16x16x32_bf16 v[98:101], v[134:137], v[166:169], v[98:101]
	v_mfma_f32_16x16x32_bf16 v[90:93], v[142:145], v[166:169], v[90:93]
	v_mfma_f32_16x16x32_bf16 v[82:85], v[134:137], v[174:177], v[82:85]
	v_mfma_f32_16x16x32_bf16 v[74:77], v[142:145], v[174:177], v[74:77]
	s_setprio 0
	s_barrier
; #define PG8_STAGE(bufoff, gbase, voff) do { _Pragma("unroll") for (int _i = 0; _i < 2; ++_i) \
;         __builtin_amdgcn_global_load_lds((const unsigned*)((const char*)(gbase) + (voff)[_i]), (LAS unsigned*)(lds + (bufoff) + ldsw + _i * 8192), 16, 0, 0); } while (0)
; #define PG8_LDA(dst, b, h) do { _Pragma("unroll") for (int m = 0; m < 4; ++m) _Pragma("unroll") for (int k = 0; k < 2; ++k) dst[m][k] = *(const LAS bf16x8*)(lds + PG8_SA(b, h) + aoff + m * 2048 + k * 1024); } while (0)
; #define PG8_LDB(dst, b, h) do { _Pragma("unroll") for (int n = 0; n < 2; ++n) _Pragma("unroll") for (int k = 0; k < 2; ++k) dst[n][k] = *(const LAS bf16x8*)(lds + PG8_SB(b, h) + boff + n * 2048 + k * 1024); } while (0)
; #define PG8_MMA(ai, bj, At, Bt) do { __builtin_amdgcn_s_setprio(1); _Pragma("unroll") for (int m = 0; m < 4; ++m) _Pragma("unroll") for (int n = 0; n < 2; ++n) _Pragma("unroll") for (int k = 0; k < 2; ++k) \
;         acc[ai][bj][m][n] = __builtin_amdgcn_mfma_f32_16x16x32_bf16(Bt[n][k], At[m][k], acc[ai][bj][m][n], 0, 0, 0); __builtin_amdgcn_s_setprio(0); } while (0)
; #define PG8_WAIT_V(n) asm volatile("s_waitcnt vmcnt(" #n ")" ::: "memory")
; #define PG8_WAIT_L(n) asm volatile("s_waitcnt lgkmcnt(" #n ")" ::: "memory")
; #define PG8_BAR __builtin_amdgcn_s_barrier()
; #define PG8_SCHED __builtin_amdgcn_sched_barrier(0)
; template <class EpiFn>
; DI void gemm_phase(LAS unsigned char* lds, const Sched& S, const bool perm, const EpiFn& E) {
;     ...
;             PG8_STAGE(PG8_SB(0, 1), b2 + hstep, voffB);
;             PG8_WAIT_V(6); PG8_BAR; PG8_MMA(1, 1, At, B1); PG8_BAR;
;             PG8_LDB(B0, 1, 0); PG8_SCHED; PG8_LDA(At, 1, 0); PG8_STAGE(PG8_SA(0, 1), a2 + hstep, voffA);
;             PG8_WAIT_L(8); PG8_BAR; PG8_WAIT_L(0); PG8_MMA(0, 0, At, B0); PG8_BAR; PG8_SCHED;
;             PG8_LDB(B1, 1, 1); PG8_STAGE(PG8_SB(1, 0), b3, voffB);
	s_add_u32 s40, s40, s92
	s_addc_u32 s41, s41, s93
	s_add_i32 s60, s60, s75
	v_lshl_add_u64 v[236:237], s[40:41], 0, v[192:193]
	s_mov_b32 m0, s60
	v_lshl_add_u64 v[238:239], s[40:41], 0, v[188:189]
	global_load_lds_dwordx4 v[236:237], off
	s_add_i32 m0, s60, 0x2000
	s_nop 0
	global_load_lds_dwordx4 v[238:239], off
	s_waitcnt vmcnt(6)
	s_barrier
	s_setprio 1
	v_mfma_f32_16x16x32_bf16 v[102:105], v[178:181], v[146:149], 0
	v_mfma_f32_16x16x32_bf16 v[94:97], v[200:203], v[146:149], 0
	v_mfma_f32_16x16x32_bf16 v[86:89], v[178:181], v[154:157], 0
	v_mfma_f32_16x16x32_bf16 v[78:81], v[200:203], v[154:157], 0
	v_mfma_f32_16x16x32_bf16 v[66:69], v[178:181], v[162:165], 0
	v_mfma_f32_16x16x32_bf16 v[62:65], v[200:203], v[162:165], 0
	v_mfma_f32_16x16x32_bf16 v[54:57], v[178:181], v[170:173], 0
	v_mfma_f32_16x16x32_bf16 v[46:49], v[200:203], v[170:173], 0
	v_mfma_f32_16x16x32_bf16 v[102:105], v[182:185], v[150:153], v[102:105]
	v_mfma_f32_16x16x32_bf16 v[94:97], v[204:207], v[150:153], v[94:97]
	v_mfma_f32_16x16x32_bf16 v[86:89], v[182:185], v[158:161], v[86:89]
	v_mfma_f32_16x16x32_bf16 v[78:81], v[204:207], v[158:161], v[78:81]
	v_mfma_f32_16x16x32_bf16 v[66:69], v[182:185], v[166:169], v[66:69]
	v_mfma_f32_16x16x32_bf16 v[62:65], v[204:207], v[166:169], v[62:65]
	v_mfma_f32_16x16x32_bf16 v[54:57], v[182:185], v[174:177], v[54:57]
	v_mfma_f32_16x16x32_bf16 v[46:49], v[204:207], v[174:177], v[46:49]
	s_setprio 0
	s_add_i32 s40, 0, 0x18000
	v_add_u32_e32 v0, s40, v222
	s_barrier
	ds_read_b128 v[130:133], v0
	ds_read_b128 v[134:137], v0 offset:1024
	ds_read_b128 v[138:141], v0 offset:2048
	ds_read_b128 v[142:145], v0 offset:3072
	s_add_u32 s8, s8, s92
	s_addc_u32 s9, s9, s93
	s_mov_b32 m0, s54
	v_lshl_add_u64 v[178:179], s[8:9], 0, v[190:191]
	ds_read_b128 v[146:149], v228 offset:32768
	ds_read_b128 v[150:153], v228 offset:33792
	ds_read_b128 v[154:157], v228 offset:34816
	ds_read_b128 v[158:161], v228 offset:35840
	ds_read_b128 v[162:165], v228 offset:36864
	ds_read_b128 v[166:169], v228 offset:37888
	ds_read_b128 v[170:173], v228 offset:38912
	ds_read_b128 v[174:177], v228 offset:39936
	global_load_lds_dwordx4 v[178:179], off
	v_lshl_add_u64 v[178:179], s[8:9], 0, v[186:187]
	s_mov_b32 m0, s33
	s_nop 0
	global_load_lds_dwordx4 v[178:179], off
	s_waitcnt lgkmcnt(8)
	s_barrier
	s_waitcnt lgkmcnt(0)
	s_setprio 1
	s_waitcnt lgkmcnt(0)
	v_mfma_f32_16x16x32_bf16 v[118:121], v[130:133], v[146:149], v[118:121]
	v_mfma_f32_16x16x32_bf16 v[106:109], v[138:141], v[146:149], v[106:109]
	v_mfma_f32_16x16x32_bf16 v[50:53], v[130:133], v[154:157], v[50:53]
	v_mfma_f32_16x16x32_bf16 v[42:45], v[138:141], v[154:157], v[42:45]
	v_mfma_f32_16x16x32_bf16 v[30:33], v[130:133], v[162:165], v[30:33]
	v_mfma_f32_16x16x32_bf16 v[26:29], v[138:141], v[162:165], v[26:29]
	v_mfma_f32_16x16x32_bf16 v[14:17], v[130:133], v[170:173], v[14:17]
	v_mfma_f32_16x16x32_bf16 v[10:13], v[138:141], v[170:173], v[10:13]
	v_mfma_f32_16x16x32_bf16 v[118:121], v[134:137], v[150:153], v[118:121]
	v_mfma_f32_16x16x32_bf16 v[106:109], v[142:145], v[150:153], v[106:109]
	v_mfma_f32_16x16x32_bf16 v[50:53], v[134:137], v[158:161], v[50:53]
	v_mfma_f32_16x16x32_bf16 v[42:45], v[142:145], v[158:161], v[42:45]
	v_mfma_f32_16x16x32_bf16 v[30:33], v[134:137], v[166:169], v[30:33]
	v_mfma_f32_16x16x32_bf16 v[26:29], v[142:145], v[166:169], v[26:29]
	v_mfma_f32_16x16x32_bf16 v[14:17], v[134:137], v[174:177], v[14:17]
	v_mfma_f32_16x16x32_bf16 v[10:13], v[142:145], v[174:177], v[10:13]
	s_setprio 0
	s_barrier
	s_add_i32 s8, 0, 0x1c000
	s_add_i32 s9, s40, s75
	v_add_u32_e32 v0, s8, v222
	v_lshl_add_u64 v[208:209], v[208:209], 0, s[64:65]
	s_mov_b32 m0, s9
	ds_read_b128 v[178:181], v0
	ds_read_b128 v[182:185], v0 offset:1024
	ds_read_b128 v[200:203], v0 offset:2048
	ds_read_b128 v[204:207], v0 offset:3072
	global_load_lds_dwordx4 v[208:209], off
	v_lshl_add_u64 v[208:209], v[230:231], 0, s[64:65]
	s_add_i32 m0, s9, 0x2000
	s_nop 0
	global_load_lds_dwordx4 v[208:209], off
	s_barrier
; #define PG8_STAGE(bufoff, gbase, voff) do { _Pragma("unroll") for (int _i = 0; _i < 2; ++_i) \
;         __builtin_amdgcn_global_load_lds((const unsigned*)((const char*)(gbase) + (voff)[_i]), (LAS unsigned*)(lds + (bufoff) + ldsw + _i * 8192), 16, 0, 0); } while (0)
; #define PG8_LDA(dst, b, h) do { _Pragma("unroll") for (int m = 0; m < 4; ++m) _Pragma("unroll") for (int k = 0; k < 2; ++k) dst[m][k] = *(const LAS bf16x8*)(lds + PG8_SA(b, h) + aoff + m * 2048 + k * 1024); } while (0)
; #define PG8_MMA(ai, bj, At, Bt) do { __builtin_amdgcn_s_setprio(1); _Pragma("unroll") for (int m = 0; m < 4; ++m) _Pragma("unroll") for (int n = 0; n < 2; ++n) _Pragma("unroll") for (int k = 0; k < 2; ++k) \
;         acc[ai][bj][m][n] = __builtin_amdgcn_mfma_f32_16x16x32_bf16(Bt[n][k], At[m][k], acc[ai][bj][m][n], 0, 0, 0); __builtin_amdgcn_s_setprio(0); } while (0)
; #define PG8_WAIT_V(n) asm volatile("s_waitcnt vmcnt(" #n ")" ::: "memory")
; #define PG8_WAIT_L(n) asm volatile("s_waitcnt lgkmcnt(" #n ")" ::: "memory")
; #define PG8_BAR __builtin_amdgcn_s_barrier()
; #define PG8_SCHED __builtin_amdgcn_sched_barrier(0)
; template <class EpiFn>
; DI void gemm_phase(LAS unsigned char* lds, const Sched& S, const bool perm, const EpiFn& E) {
;     ...
;             PG8_BAR; PG8_WAIT_L(0); PG8_MMA(0, 1, At, B1); PG8_BAR;
;             PG8_LDA(At, 1, 1); PG8_STAGE(PG8_SA(1, 0), a3, voffA);
;             PG8_BAR; PG8_WAIT_L(0); PG8_MMA(1, 0, At, B0); PG8_BAR; PG8_SCHED;
;             PG8_STAGE(PG8_SB(1, 1), b3 + hstep, voffB);
;             PG8_WAIT_V(6); PG8_BAR; PG8_MMA(1, 1, At, B1); PG8_BAR;
;         }
	s_waitcnt lgkmcnt(0)
	s_setprio 1
	s_waitcnt lgkmcnt(0)
	v_mfma_f32_16x16x32_bf16 v[70:73], v[178:181], v[146:149], v[70:73]
	v_mfma_f32_16x16x32_bf16 v[58:61], v[200:203], v[146:149], v[58:61]
	v_mfma_f32_16x16x32_bf16 v[38:41], v[178:181], v[154:157], v[38:41]
	v_mfma_f32_16x16x32_bf16 v[34:37], v[200:203], v[154:157], v[34:37]
	v_mfma_f32_16x16x32_bf16 v[22:25], v[178:181], v[162:165], v[22:25]
	v_mfma_f32_16x16x32_bf16 v[18:21], v[200:203], v[162:165], v[18:21]
	v_mfma_f32_16x16x32_bf16 v[6:9], v[178:181], v[170:173], v[6:9]
	v_mfma_f32_16x16x32_bf16 v[2:5], v[200:203], v[170:173], v[2:5]
	v_mfma_f32_16x16x32_bf16 v[70:73], v[182:185], v[150:153], v[70:73]
	v_mfma_f32_16x16x32_bf16 v[58:61], v[204:207], v[150:153], v[58:61]
	v_mfma_f32_16x16x32_bf16 v[38:41], v[182:185], v[158:161], v[38:41]
	v_mfma_f32_16x16x32_bf16 v[34:37], v[204:207], v[158:161], v[34:37]
	v_mfma_f32_16x16x32_bf16 v[22:25], v[182:185], v[166:169], v[22:25]
	v_mfma_f32_16x16x32_bf16 v[18:21], v[204:207], v[166:169], v[18:21]
	v_mfma_f32_16x16x32_bf16 v[6:9], v[182:185], v[174:177], v[6:9]
	v_mfma_f32_16x16x32_bf16 v[2:5], v[204:207], v[174:177], v[2:5]
	s_setprio 0
	s_mov_b32 m0, s59
	v_lshl_add_u64 v[208:209], v[232:233], 0, s[64:65]
	s_barrier
	ds_read_b128 v[146:149], v228 offset:49152
	ds_read_b128 v[150:153], v228 offset:50176
	ds_read_b128 v[154:157], v228 offset:51200
	ds_read_b128 v[158:161], v228 offset:52224
	ds_read_b128 v[162:165], v228 offset:53248
	ds_read_b128 v[166:169], v228 offset:54272
	ds_read_b128 v[170:173], v228 offset:55296
	ds_read_b128 v[174:177], v228 offset:56320
	global_load_lds_dwordx4 v[208:209], off
	v_lshl_add_u64 v[208:209], v[234:235], 0, s[64:65]
	s_mov_b32 m0, s44
	s_nop 0
	global_load_lds_dwordx4 v[208:209], off
	s_barrier
	s_waitcnt lgkmcnt(0)
	s_setprio 1
	s_waitcnt lgkmcnt(0)
	v_mfma_f32_16x16x32_bf16 v[126:129], v[130:133], v[146:149], v[126:129]
	v_mfma_f32_16x16x32_bf16 v[122:125], v[138:141], v[146:149], v[122:125]
	v_mfma_f32_16x16x32_bf16 v[114:117], v[130:133], v[154:157], v[114:117]
	v_mfma_f32_16x16x32_bf16 v[110:113], v[138:141], v[154:157], v[110:113]
	v_mfma_f32_16x16x32_bf16 v[98:101], v[130:133], v[162:165], v[98:101]
	v_mfma_f32_16x16x32_bf16 v[90:93], v[138:141], v[162:165], v[90:93]
	v_mfma_f32_16x16x32_bf16 v[82:85], v[130:133], v[170:173], v[82:85]
	v_mfma_f32_16x16x32_bf16 v[74:77], v[138:141], v[170:173], v[74:77]
	v_mfma_f32_16x16x32_bf16 v[126:129], v[134:137], v[150:153], v[126:129]
	v_mfma_f32_16x16x32_bf16 v[122:125], v[142:145], v[150:153], v[122:125]
	v_mfma_f32_16x16x32_bf16 v[114:117], v[134:137], v[158:161], v[114:117]
	v_mfma_f32_16x16x32_bf16 v[110:113], v[142:145], v[158:161], v[110:113]
	v_mfma_f32_16x16x32_bf16 v[98:101], v[134:137], v[166:169], v[98:101]
	v_mfma_f32_16x16x32_bf16 v[90:93], v[142:145], v[166:169], v[90:93]
	v_mfma_f32_16x16x32_bf16 v[82:85], v[134:137], v[174:177], v[82:85]
	v_mfma_f32_16x16x32_bf16 v[74:77], v[142:145], v[174:177], v[74:77]
	s_setprio 0
	s_barrier
	s_add_i32 s8, s8, s75
	v_lshl_add_u64 v[130:131], v[236:237], 0, s[64:65]
	s_mov_b32 m0, s8
	s_nop 0
	global_load_lds_dwordx4 v[130:131], off
	v_lshl_add_u64 v[130:131], v[238:239], 0, s[64:65]
	s_add_i32 m0, s8, 0x2000
	s_nop 0
	global_load_lds_dwordx4 v[130:131], off
	s_waitcnt vmcnt(6)
	s_barrier
	s_setprio 1
	v_mfma_f32_16x16x32_bf16 v[102:105], v[178:181], v[146:149], v[102:105]
	v_mfma_f32_16x16x32_bf16 v[94:97], v[200:203], v[146:149], v[94:97]
	v_mfma_f32_16x16x32_bf16 v[86:89], v[178:181], v[154:157], v[86:89]
	v_mfma_f32_16x16x32_bf16 v[78:81], v[200:203], v[154:157], v[78:81]
	v_mfma_f32_16x16x32_bf16 v[66:69], v[178:181], v[162:165], v[66:69]
	v_mfma_f32_16x16x32_bf16 v[62:65], v[200:203], v[162:165], v[62:65]
	v_mfma_f32_16x16x32_bf16 v[54:57], v[178:181], v[170:173], v[54:57]
	v_mfma_f32_16x16x32_bf16 v[46:49], v[200:203], v[170:173], v[46:49]
	v_mfma_f32_16x16x32_bf16 v[102:105], v[182:185], v[150:153], v[102:105]
	v_mfma_f32_16x16x32_bf16 v[94:97], v[204:207], v[150:153], v[94:97]
	v_mfma_f32_16x16x32_bf16 v[86:89], v[182:185], v[158:161], v[86:89]
	v_mfma_f32_16x16x32_bf16 v[78:81], v[204:207], v[158:161], v[78:81]
	v_mfma_f32_16x16x32_bf16 v[66:69], v[182:185], v[166:169], v[66:69]
	v_mfma_f32_16x16x32_bf16 v[62:65], v[204:207], v[166:169], v[62:65]
	v_mfma_f32_16x16x32_bf16 v[54:57], v[182:185], v[174:177], v[54:57]
	v_mfma_f32_16x16x32_bf16 v[46:49], v[204:207], v[174:177], v[46:49]
	s_setprio 0
	s_add_u32 s6, s6, 0x100
	s_addc_u32 s7, s7, 0
	s_add_u32 s18, s18, 0x100
	s_addc_u32 s51, s51, 0
	s_cmp_ge_u32 s61, s16
	s_mov_b32 s60, s61
	s_barrier
	s_cbranch_scc1 .Lgemm_trips_done

; DI float sigmoidf_(float x) { return __builtin_amdgcn_rcpf(1.f + __builtin_amdgcn_exp2f(-LOG2E * x)); }
; DI void st_bf16x8(bf16_t* p, f32x4 a, f32x4 b) { u32x4 o; o[0] = cvtpk(a[0], a[1]); o[1] = cvtpk(a[2], a[3]); o[2] = cvtpk(b[0], b[1]); o[3] = cvtpk(b[2], b[3]); *(u32x4*)p = o; }
;     DI void operator()(const Acc& acc, const Unit& u, int wr, int wc, int fr, int fq) const {
;         const int row0 = u.pm * 256 + wr * 64 + fr, col0 = u.pn * 128 + wc * 32 + 8 * fq;
; #pragma unroll
;         for (int ai = 0; ai < 2; ++ai)
; #pragma unroll
;             for (int m = 0; m < 4; ++m) {
;                 int r = row0 + ai * 128 + m * 16; asm volatile("" : "+v"(r));
;                 f32x4 v[2];
; #pragma unroll
;                 for (int n = 0; n < 2; ++n)
; #pragma unroll
;                     for (int j = 0; j < 4; ++j) { const float g = acc[ai][1][m][n][j]; v[n][j] = g * sigmoidf_(g) * acc[ai][0][m][n][j]; }
;                 st_bf16x8(hid + (size_t)r * DFF + col0, v[0], v[1]);
;             }
;     }
;     DI void operator()(const Acc& acc, const Unit& u, int wr, int wc, int fr, int fq) const {
;         unsigned char* ws = p->ws;
;         switch (epi) {
;         case EPI_MOD: { EpiMod E{(float*)(ws + WS_MOD), p->in[9]}; E(acc, u, wr, wc, fr, fq); break; }
;         case EPI_IN: { EpiIn E{(bf16_t*)(ws + WS_ZQK), (bf16_t*)(ws + WS_ZS), (bf16_t*)(ws + WS_G), (bf16_t*)(ws + WS_VT), p->out, l}; E(acc, u, wr, wc, fr, fq); break; }
;         case EPI_LR: { EpiLr E{(bf16_t*)(ws + WS_LRO), p->in[14] + (size_t)l * 512, p->in[16] + (size_t)l * 512}; E(acc, u, wr, wc, fr, fq); break; }
;         case EPI_MRG0: { EpiMerge<0> E{(const bf16_t*)(ws + WS_G), (bf16_t*)(ws + WS_TMP), (bf16_t*)(ws + WS_MRG)}; E(acc, u, wr, wc, fr, fq); break; }
;         case EPI_MRG1: { EpiMerge<1> E{(const bf16_t*)(ws + WS_G), (bf16_t*)(ws + WS_TMP), (bf16_t*)(ws + WS_MRG)}; E(acc, u, wr, wc, fr, fq); break; }
;         case EPI_RES1: { EpiRes E{p->out, (const float*)(ws + WS_MOD) + (size_t)l * 6144 + 2048, (float*)(ws + WS_SLAB)}; E(acc, u, wr, wc, fr, fq); break; }
;         case EPI_FFN: { EpiFfn E{(bf16_t*)(ws + WS_HID)}; E(acc, u, wr, wc, fr, fq); break; }
.Lgemm_trips_done:
	s_mov_b64 s[8:9], -1
	s_mov_b64 s[6:7], 0
	s_cmp_lt_i32 s25, 3
	s_mov_b64 s[40:41], 0
	s_cbranch_scc1 .LBB0_415
	s_cmp_gt_i32 s25, 4
	s_cbranch_scc0 .LBB0_409
	s_cmp_gt_i32 s25, 5
	s_cbranch_scc0 .LBB0_402
	s_cmp_eq_u32 s25, 6
	s_mov_b64 s[40:41], -1
	s_cbranch_scc0 .LBB0_401
	v_mul_f32_e32 v136, 0xbfb8aa3b, v73
	v_exp_f32_e32 v136, v136
	v_mul_f32_e32 v137, 0xbfb8aa3b, v58
	v_exp_f32_e32 v137, v137
	v_mul_f32_e32 v138, 0xbfb8aa3b, v59
	v_add_f32_e32 v136, 1.0, v136
	v_rcp_f32_e32 v136, v136
	v_add_f32_e32 v137, 1.0, v137
	v_rcp_f32_e32 v137, v137
	v_exp_f32_e32 v138, v138
	v_mul_f32_e32 v136, v73, v136
	v_mul_f32_e32 v139, v121, v136
	v_mul_f32_e32 v136, v58, v137
	v_mul_f32_e32 v137, 0xbfb8aa3b, v60
	v_mul_f32_e32 v132, 0xbfb8aa3b, v70
	v_mul_f32_e32 v133, 0xbfb8aa3b, v71
	v_mul_f32_e32 v135, 0xbfb8aa3b, v72
	v_mul_f32_e32 v140, v106, v136
	v_add_f32_e32 v136, 1.0, v138
	v_exp_f32_e32 v137, v137
	v_mul_f32_e32 v138, 0xbfb8aa3b, v61
	v_exp_f32_e32 v132, v132
	v_exp_f32_e32 v133, v133
	v_exp_f32_e32 v135, v135
	v_exp_f32_e32 v138, v138
	v_rcp_f32_e32 v136, v136
	v_add_f32_e32 v137, 1.0, v137
	v_add_f32_e32 v132, 1.0, v132
	v_add_f32_e32 v133, 1.0, v133
	v_add_f32_e32 v135, 1.0, v135
	v_rcp_f32_e32 v137, v137
	v_add_f32_e32 v138, 1.0, v138
	v_rcp_f32_e32 v132, v132
	v_rcp_f32_e32 v133, v133
	v_rcp_f32_e32 v135, v135
	v_rcp_f32_e32 v138, v138
	v_lshl_or_b32 v130, s46, 7, v223
	v_mul_f32_e32 v136, v59, v136
	v_lshl_add_u32 v0, s97, 8, v220
	v_ashrrev_i32_e32 v131, 31, v130
	v_mul_f32_e32 v141, v107, v136
	v_mul_f32_e32 v136, v60, v137
	v_lshl_add_u64 v[130:131], v[130:131], 1, s[30:31]
	v_mov_b32_e32 v134, v0
	v_mul_f32_e32 v132, v70, v132
	v_mul_f32_e32 v133, v71, v133
	v_mul_f32_e32 v135, v72, v135
	v_mul_f32_e32 v142, v108, v136
	v_mul_f32_e32 v136, v61, v138
	s_movk_i32 s16, 0x1600
	v_mul_f32_e32 v132, v118, v132
	v_mul_f32_e32 v133, v119, v133
	v_mul_f32_e32 v135, v120, v135
	v_mul_f32_e32 v138, v109, v136
	v_mad_i64_i32 v[136:137], s[8:9], v134, s16, v[130:131]
	v_cvt_pk_bf16_f32 v132, v132, v133
	v_cvt_pk_bf16_f32 v133, v135, v139
	v_cvt_pk_bf16_f32 v134, v140, v141
	v_cvt_pk_bf16_f32 v135, v142, v138
	global_store_dwordx4 v[136:137], v[132:135], off
	v_mul_f32_e32 v136, 0xbfb8aa3b, v41
	v_exp_f32_e32 v136, v136
	v_mul_f32_e32 v137, 0xbfb8aa3b, v34
	v_exp_f32_e32 v137, v137
	v_mul_f32_e32 v138, 0xbfb8aa3b, v35
	v_add_f32_e32 v136, 1.0, v136
	v_rcp_f32_e32 v136, v136
	v_add_f32_e32 v137, 1.0, v137
	v_rcp_f32_e32 v137, v137
	v_exp_f32_e32 v138, v138
	v_mul_f32_e32 v136, v41, v136
	v_mul_f32_e32 v139, v53, v136
	v_mul_f32_e32 v136, v34, v137
	v_mul_f32_e32 v137, 0xbfb8aa3b, v36
	v_mul_f32_e32 v132, 0xbfb8aa3b, v38
	v_mul_f32_e32 v133, 0xbfb8aa3b, v39
	v_mul_f32_e32 v135, 0xbfb8aa3b, v40
	v_mul_f32_e32 v140, v42, v136
	v_add_f32_e32 v136, 1.0, v138
	v_exp_f32_e32 v137, v137
	v_mul_f32_e32 v138, 0xbfb8aa3b, v37
	v_exp_f32_e32 v132, v132
	v_exp_f32_e32 v133, v133
	v_exp_f32_e32 v135, v135
	v_exp_f32_e32 v138, v138
	v_rcp_f32_e32 v136, v136
	v_add_f32_e32 v137, 1.0, v137
	v_add_f32_e32 v132, 1.0, v132
	v_add_f32_e32 v133, 1.0, v133
	v_add_f32_e32 v135, 1.0, v135
	v_rcp_f32_e32 v137, v137
	v_add_f32_e32 v138, 1.0, v138
	v_rcp_f32_e32 v132, v132
	v_rcp_f32_e32 v133, v133
	v_rcp_f32_e32 v135, v135
	v_rcp_f32_e32 v138, v138
	v_mul_f32_e32 v136, v35, v136
	v_mul_f32_e32 v141, v43, v136
	v_mul_f32_e32 v136, v36, v137
	v_or_b32_e32 v134, 16, v0
	v_mul_f32_e32 v132, v38, v132
	v_mul_f32_e32 v133, v39, v133
	v_mul_f32_e32 v135, v40, v135
	v_mul_f32_e32 v142, v44, v136
	v_mul_f32_e32 v136, v37, v138
	v_mul_f32_e32 v132, v50, v132
	v_mul_f32_e32 v133, v51, v133
	v_mul_f32_e32 v135, v52, v135
	v_mul_f32_e32 v138, v45, v136
	v_mad_i64_i32 v[136:137], s[8:9], v134, s16, v[130:131]
	v_cvt_pk_bf16_f32 v132, v132, v133
	v_cvt_pk_bf16_f32 v133, v135, v139
	v_cvt_pk_bf16_f32 v134, v140, v141
	v_cvt_pk_bf16_f32 v135, v142, v138
	global_store_dwordx4 v[136:137], v[132:135], off
	v_mul_f32_e32 v136, 0xbfb8aa3b, v25
	v_exp_f32_e32 v136, v136
	v_mul_f32_e32 v137, 0xbfb8aa3b, v18
	v_exp_f32_e32 v137, v137
	v_mul_f32_e32 v138, 0xbfb8aa3b, v19
	v_add_f32_e32 v136, 1.0, v136
	v_rcp_f32_e32 v136, v136
	v_add_f32_e32 v137, 1.0, v137
	v_rcp_f32_e32 v137, v137
	v_exp_f32_e32 v138, v138
	v_mul_f32_e32 v136, v25, v136
	v_mul_f32_e32 v139, v33, v136
	v_mul_f32_e32 v136, v18, v137
	v_mul_f32_e32 v137, 0xbfb8aa3b, v20
	v_mul_f32_e32 v132, 0xbfb8aa3b, v22
	v_mul_f32_e32 v133, 0xbfb8aa3b, v23
	v_mul_f32_e32 v135, 0xbfb8aa3b, v24
	v_mul_f32_e32 v140, v26, v136
	v_add_f32_e32 v136, 1.0, v138
	v_exp_f32_e32 v137, v137
	v_mul_f32_e32 v138, 0xbfb8aa3b, v21
	v_exp_f32_e32 v132, v132
	v_exp_f32_e32 v133, v133
	v_exp_f32_e32 v135, v135
	v_exp_f32_e32 v138, v138
	v_rcp_f32_e32 v136, v136
	v_add_f32_e32 v137, 1.0, v137
	v_add_f32_e32 v132, 1.0, v132
	v_add_f32_e32 v133, 1.0, v133
	v_add_f32_e32 v135, 1.0, v135
	v_rcp_f32_e32 v137, v137
	v_add_f32_e32 v138, 1.0, v138
	v_rcp_f32_e32 v132, v132
	v_rcp_f32_e32 v133, v133
	v_rcp_f32_e32 v135, v135
	v_rcp_f32_e32 v138, v138
	v_mul_f32_e32 v136, v19, v136
	v_mul_f32_e32 v141, v27, v136
	v_mul_f32_e32 v136, v20, v137
	v_or_b32_e32 v134, 32, v0
	v_mul_f32_e32 v132, v22, v132
	v_mul_f32_e32 v133, v23, v133
	v_mul_f32_e32 v135, v24, v135
	v_mul_f32_e32 v142, v28, v136
	v_mul_f32_e32 v136, v21, v138
	v_mul_f32_e32 v132, v30, v132
	v_mul_f32_e32 v133, v31, v133
	v_mul_f32_e32 v135, v32, v135
	v_mul_f32_e32 v138, v29, v136
	v_mad_i64_i32 v[136:137], s[8:9], v134, s16, v[130:131]
	v_cvt_pk_bf16_f32 v132, v132, v133
	v_cvt_pk_bf16_f32 v133, v135, v139
	v_cvt_pk_bf16_f32 v134, v140, v141
	v_cvt_pk_bf16_f32 v135, v142, v138
; DI float sigmoidf_(float x) { return __builtin_amdgcn_rcpf(1.f + __builtin_amdgcn_exp2f(-LOG2E * x)); }
; DI void st_bf16x8(bf16_t* p, f32x4 a, f32x4 b) { u32x4 o; o[0] = cvtpk(a[0], a[1]); o[1] = cvtpk(a[2], a[3]); o[2] = cvtpk(b[0], b[1]); o[3] = cvtpk(b[2], b[3]); *(u32x4*)p = o; }
;     DI void operator()(const Acc& acc, const Unit& u, int wr, int wc, int fr, int fq) const {
;     ...
;                 int r = row0 + ai * 128 + m * 16; asm volatile("" : "+v"(r));
;                 f32x4 v[2];
; #pragma unroll
;                 for (int n = 0; n < 2; ++n)
; #pragma unroll
;                     for (int j = 0; j < 4; ++j) { const float g = acc[ai][1][m][n][j]; v[n][j] = g * sigmoidf_(g) * acc[ai][0][m][n][j]; }
;                 st_bf16x8(hid + (size_t)r * DFF + col0, v[0], v[1]);
	global_store_dwordx4 v[136:137], v[132:135], off
	v_mul_f32_e32 v136, 0xbfb8aa3b, v9
	v_exp_f32_e32 v136, v136
	v_mul_f32_e32 v137, 0xbfb8aa3b, v2
	v_exp_f32_e32 v137, v137
	v_mul_f32_e32 v138, 0xbfb8aa3b, v3
	v_add_f32_e32 v136, 1.0, v136
	v_rcp_f32_e32 v136, v136
	v_add_f32_e32 v137, 1.0, v137
	v_rcp_f32_e32 v137, v137
	v_exp_f32_e32 v138, v138
	v_mul_f32_e32 v136, v9, v136
	v_mul_f32_e32 v139, v17, v136
	v_mul_f32_e32 v136, v2, v137
	v_mul_f32_e32 v137, 0xbfb8aa3b, v4
	v_mul_f32_e32 v132, 0xbfb8aa3b, v6
	v_mul_f32_e32 v133, 0xbfb8aa3b, v7
	v_mul_f32_e32 v135, 0xbfb8aa3b, v8
	v_mul_f32_e32 v140, v10, v136
	v_add_f32_e32 v136, 1.0, v138
	v_exp_f32_e32 v137, v137
	v_mul_f32_e32 v138, 0xbfb8aa3b, v5
	v_exp_f32_e32 v132, v132
	v_exp_f32_e32 v133, v133
	v_exp_f32_e32 v135, v135
	v_exp_f32_e32 v138, v138
	v_rcp_f32_e32 v136, v136
	v_add_f32_e32 v137, 1.0, v137
	v_add_f32_e32 v132, 1.0, v132
	v_add_f32_e32 v133, 1.0, v133
	v_add_f32_e32 v135, 1.0, v135
	v_rcp_f32_e32 v137, v137
	v_add_f32_e32 v138, 1.0, v138
	v_rcp_f32_e32 v132, v132
	v_rcp_f32_e32 v133, v133
	v_rcp_f32_e32 v135, v135
	v_rcp_f32_e32 v138, v138
	v_mul_f32_e32 v136, v3, v136
	v_mul_f32_e32 v141, v11, v136
	v_mul_f32_e32 v136, v4, v137
	v_or_b32_e32 v134, 48, v0
	v_mul_f32_e32 v132, v6, v132
	v_mul_f32_e32 v133, v7, v133
	v_mul_f32_e32 v135, v8, v135
	v_mul_f32_e32 v142, v12, v136
	v_mul_f32_e32 v136, v5, v138
	v_mul_f32_e32 v132, v14, v132
	v_mul_f32_e32 v133, v15, v133
	v_mul_f32_e32 v135, v16, v135
	v_mul_f32_e32 v138, v13, v136
	v_mad_i64_i32 v[136:137], s[8:9], v134, s16, v[130:131]
	v_cvt_pk_bf16_f32 v132, v132, v133
	v_cvt_pk_bf16_f32 v133, v135, v139
	v_cvt_pk_bf16_f32 v134, v140, v141
	v_cvt_pk_bf16_f32 v135, v142, v138
	global_store_dwordx4 v[136:137], v[132:135], off
	v_mul_f32_e32 v136, 0xbfb8aa3b, v105
	v_exp_f32_e32 v136, v136
	v_mul_f32_e32 v137, 0xbfb8aa3b, v94
	v_exp_f32_e32 v137, v137
	v_mul_f32_e32 v138, 0xbfb8aa3b, v95
	v_add_f32_e32 v136, 1.0, v136
	v_rcp_f32_e32 v136, v136
	v_add_f32_e32 v137, 1.0, v137
	v_rcp_f32_e32 v137, v137
	v_exp_f32_e32 v138, v138
	v_mul_f32_e32 v136, v105, v136
	v_mul_f32_e32 v139, v129, v136
	v_mul_f32_e32 v136, v94, v137
	v_mul_f32_e32 v137, 0xbfb8aa3b, v96
	v_mul_f32_e32 v132, 0xbfb8aa3b, v102
	v_mul_f32_e32 v133, 0xbfb8aa3b, v103
	v_mul_f32_e32 v135, 0xbfb8aa3b, v104
	v_mul_f32_e32 v140, v122, v136
	v_add_f32_e32 v136, 1.0, v138
	v_exp_f32_e32 v137, v137
	v_mul_f32_e32 v138, 0xbfb8aa3b, v97
	v_exp_f32_e32 v132, v132
	v_exp_f32_e32 v133, v133
	v_exp_f32_e32 v135, v135
	v_exp_f32_e32 v138, v138
	v_rcp_f32_e32 v136, v136
	v_add_f32_e32 v137, 1.0, v137
	v_add_f32_e32 v132, 1.0, v132
	v_add_f32_e32 v133, 1.0, v133
	v_add_f32_e32 v135, 1.0, v135
	v_rcp_f32_e32 v137, v137
	v_add_f32_e32 v138, 1.0, v138
	v_rcp_f32_e32 v132, v132
	v_rcp_f32_e32 v133, v133
	v_rcp_f32_e32 v135, v135
	v_rcp_f32_e32 v138, v138
	v_mul_f32_e32 v136, v95, v136
	v_mul_f32_e32 v141, v123, v136
	v_mul_f32_e32 v136, v96, v137
	v_add_u32_e32 v134, 0x80, v0
	v_mul_f32_e32 v132, v102, v132
	v_mul_f32_e32 v133, v103, v133
	v_mul_f32_e32 v135, v104, v135
	v_mul_f32_e32 v142, v124, v136
	v_mul_f32_e32 v136, v97, v138
	v_mul_f32_e32 v132, v126, v132
	v_mul_f32_e32 v133, v127, v133
	v_mul_f32_e32 v135, v128, v135
	v_mul_f32_e32 v138, v125, v136
	v_mad_i64_i32 v[136:137], s[8:9], v134, s16, v[130:131]
	v_cvt_pk_bf16_f32 v132, v132, v133
	v_cvt_pk_bf16_f32 v133, v135, v139
	v_cvt_pk_bf16_f32 v134, v140, v141
	v_cvt_pk_bf16_f32 v135, v142, v138
	global_store_dwordx4 v[136:137], v[132:135], off
	v_mul_f32_e32 v136, 0xbfb8aa3b, v89
	v_exp_f32_e32 v136, v136
	v_mul_f32_e32 v137, 0xbfb8aa3b, v78
	v_exp_f32_e32 v137, v137
	v_mul_f32_e32 v138, 0xbfb8aa3b, v79
	v_add_f32_e32 v136, 1.0, v136
	v_rcp_f32_e32 v136, v136
	v_add_f32_e32 v137, 1.0, v137
	v_rcp_f32_e32 v137, v137
	v_exp_f32_e32 v138, v138
	v_mul_f32_e32 v136, v89, v136
	v_mul_f32_e32 v139, v117, v136
	v_mul_f32_e32 v136, v78, v137
	v_mul_f32_e32 v137, 0xbfb8aa3b, v80
	v_mul_f32_e32 v132, 0xbfb8aa3b, v86
	v_mul_f32_e32 v133, 0xbfb8aa3b, v87
	v_mul_f32_e32 v135, 0xbfb8aa3b, v88
	v_mul_f32_e32 v140, v110, v136
	v_add_f32_e32 v136, 1.0, v138
	v_exp_f32_e32 v137, v137
	v_mul_f32_e32 v138, 0xbfb8aa3b, v81
	v_exp_f32_e32 v132, v132
	v_exp_f32_e32 v133, v133
	v_exp_f32_e32 v135, v135
	v_exp_f32_e32 v138, v138
	v_rcp_f32_e32 v136, v136
	v_add_f32_e32 v137, 1.0, v137
	v_add_f32_e32 v132, 1.0, v132
; DI float sigmoidf_(float x) { return __builtin_amdgcn_rcpf(1.f + __builtin_amdgcn_exp2f(-LOG2E * x)); }
; DI void st_bf16x8(bf16_t* p, f32x4 a, f32x4 b) { u32x4 o; o[0] = cvtpk(a[0], a[1]); o[1] = cvtpk(a[2], a[3]); o[2] = cvtpk(b[0], b[1]); o[3] = cvtpk(b[2], b[3]); *(u32x4*)p = o; }
;     DI void operator()(const Acc& acc, const Unit& u, int wr, int wc, int fr, int fq) const {
;     ...
;                 int r = row0 + ai * 128 + m * 16; asm volatile("" : "+v"(r));
;                 f32x4 v[2];
; #pragma unroll
;                 for (int n = 0; n < 2; ++n)
; #pragma unroll
;                     for (int j = 0; j < 4; ++j) { const float g = acc[ai][1][m][n][j]; v[n][j] = g * sigmoidf_(g) * acc[ai][0][m][n][j]; }
;                 st_bf16x8(hid + (size_t)r * DFF + col0, v[0], v[1]);
;             }
	v_add_f32_e32 v133, 1.0, v133
	v_add_f32_e32 v135, 1.0, v135
	v_rcp_f32_e32 v137, v137
	v_add_f32_e32 v138, 1.0, v138
	v_rcp_f32_e32 v132, v132
	v_rcp_f32_e32 v133, v133
	v_rcp_f32_e32 v135, v135
	v_rcp_f32_e32 v138, v138
	v_mul_f32_e32 v136, v79, v136
	v_mul_f32_e32 v141, v111, v136
	v_mul_f32_e32 v136, v80, v137
	v_add_u32_e32 v134, 0x90, v0
	v_mul_f32_e32 v132, v86, v132
	v_mul_f32_e32 v133, v87, v133
	v_mul_f32_e32 v135, v88, v135
	v_mul_f32_e32 v142, v112, v136
	v_mul_f32_e32 v136, v81, v138
	v_mul_f32_e32 v132, v114, v132
	v_mul_f32_e32 v133, v115, v133
	v_mul_f32_e32 v135, v116, v135
	v_mul_f32_e32 v138, v113, v136
	v_mad_i64_i32 v[136:137], s[8:9], v134, s16, v[130:131]
	v_cvt_pk_bf16_f32 v132, v132, v133
	v_cvt_pk_bf16_f32 v133, v135, v139
	v_cvt_pk_bf16_f32 v134, v140, v141
	v_cvt_pk_bf16_f32 v135, v142, v138
	global_store_dwordx4 v[136:137], v[132:135], off
	v_mul_f32_e32 v136, 0xbfb8aa3b, v69
	v_exp_f32_e32 v136, v136
	v_mul_f32_e32 v137, 0xbfb8aa3b, v62
	v_exp_f32_e32 v137, v137
	v_mul_f32_e32 v138, 0xbfb8aa3b, v63
	v_add_f32_e32 v136, 1.0, v136
	v_rcp_f32_e32 v136, v136
	v_add_f32_e32 v137, 1.0, v137
	v_rcp_f32_e32 v137, v137
	v_exp_f32_e32 v138, v138
	v_mul_f32_e32 v136, v69, v136
	v_mul_f32_e32 v132, 0xbfb8aa3b, v66
	v_mul_f32_e32 v133, 0xbfb8aa3b, v67
	v_mul_f32_e32 v139, v101, v136
	v_mul_f32_e32 v136, v62, v137
	v_mul_f32_e32 v137, 0xbfb8aa3b, v64
	v_exp_f32_e32 v132, v132
	v_exp_f32_e32 v133, v133
	v_mul_f32_e32 v135, 0xbfb8aa3b, v68
	v_mul_f32_e32 v140, v90, v136
	v_add_f32_e32 v136, 1.0, v138
	v_exp_f32_e32 v137, v137
	v_mul_f32_e32 v138, 0xbfb8aa3b, v65
	v_exp_f32_e32 v135, v135
	v_exp_f32_e32 v138, v138
	v_add_f32_e32 v132, 1.0, v132
	v_add_f32_e32 v133, 1.0, v133
	v_rcp_f32_e32 v136, v136
	v_add_f32_e32 v137, 1.0, v137
	v_rcp_f32_e32 v132, v132
	v_rcp_f32_e32 v133, v133
	v_add_f32_e32 v135, 1.0, v135
	v_rcp_f32_e32 v137, v137
	v_add_f32_e32 v138, 1.0, v138
	v_rcp_f32_e32 v135, v135
	v_rcp_f32_e32 v138, v138
	v_mul_f32_e32 v136, v63, v136
	v_add_u32_e32 v134, 0xa0, v0
	v_mul_f32_e32 v132, v66, v132
	v_mul_f32_e32 v133, v67, v133
	v_mul_f32_e32 v141, v91, v136
	v_mul_f32_e32 v136, v64, v137
	v_mul_f32_e32 v132, v98, v132
	v_mul_f32_e32 v133, v99, v133
	v_mul_f32_e32 v135, v68, v135
	v_mul_f32_e32 v142, v92, v136
	v_mul_f32_e32 v136, v65, v138
	v_mul_f32_e32 v135, v100, v135
	v_mul_f32_e32 v138, v93, v136
	v_mad_i64_i32 v[136:137], s[8:9], v134, s16, v[130:131]
	v_cvt_pk_bf16_f32 v132, v132, v133
	v_cvt_pk_bf16_f32 v133, v135, v139
	v_cvt_pk_bf16_f32 v134, v140, v141
	v_cvt_pk_bf16_f32 v135, v142, v138
	global_store_dwordx4 v[136:137], v[132:135], off
	v_mul_f32_e32 v136, 0xbfb8aa3b, v46
	v_exp_f32_e32 v136, v136
	v_mul_f32_e32 v134, 0xbfb8aa3b, v56
	v_exp_f32_e32 v134, v134
	v_mul_f32_e32 v135, 0xbfb8aa3b, v57
	v_exp_f32_e32 v135, v135
	v_mul_f32_e32 v132, 0xbfb8aa3b, v54
	v_add_f32_e32 v134, 1.0, v134
	v_rcp_f32_e32 v134, v134
	v_add_f32_e32 v135, 1.0, v135
	v_rcp_f32_e32 v135, v135
	v_mul_f32_e32 v133, 0xbfb8aa3b, v55
	v_mul_f32_e32 v134, v56, v134
	v_mul_f32_e32 v137, v84, v134
	v_mul_f32_e32 v134, v57, v135
	v_add_f32_e32 v135, 1.0, v136
	v_rcp_f32_e32 v135, v135
	v_mul_f32_e32 v136, 0xbfb8aa3b, v47
	v_exp_f32_e32 v136, v136
	v_mul_f32_e32 v138, v85, v134
	v_mul_f32_e32 v134, v46, v135
	v_mul_f32_e32 v135, 0xbfb8aa3b, v48
	v_mul_f32_e32 v139, v74, v134
	v_add_f32_e32 v134, 1.0, v136
	v_exp_f32_e32 v135, v135
	v_mul_f32_e32 v136, 0xbfb8aa3b, v49
	v_exp_f32_e32 v132, v132
	v_exp_f32_e32 v133, v133
	v_exp_f32_e32 v136, v136
	v_rcp_f32_e32 v134, v134
	v_add_f32_e32 v135, 1.0, v135
	v_add_f32_e32 v132, 1.0, v132
	v_add_f32_e32 v133, 1.0, v133
	v_rcp_f32_e32 v135, v135
	v_add_f32_e32 v136, 1.0, v136
	v_rcp_f32_e32 v132, v132
	v_rcp_f32_e32 v133, v133
	v_rcp_f32_e32 v136, v136
	v_mul_f32_e32 v134, v47, v134
	v_mul_f32_e32 v140, v75, v134
	v_mul_f32_e32 v134, v48, v135
	v_add_u32_e32 v0, 0xb0, v0
	v_mul_f32_e32 v132, v54, v132
	v_mul_f32_e32 v133, v55, v133
	v_mul_f32_e32 v141, v76, v134
	v_mul_f32_e32 v134, v49, v136
	v_mul_f32_e32 v132, v82, v132
	v_mul_f32_e32 v133, v83, v133
	v_mul_f32_e32 v136, v77, v134
	v_mad_i64_i32 v[134:135], s[8:9], v0, s16, v[130:131]
	v_cvt_pk_bf16_f32 v130, v132, v133
	v_cvt_pk_bf16_f32 v131, v137, v138
	v_cvt_pk_bf16_f32 v132, v139, v140
	v_cvt_pk_bf16_f32 v133, v141, v136
	global_store_dwordx4 v[134:135], v[130:133], off
	s_mov_b64 s[40:41], 0
